# v9: v8 + MLP-up K-loop load segments made VALU-free (saddr-form LDS-DMA, one precomputed LDS base VGPR with immediate offsets)
# baseline (speedup 1.0000x reference)
.LBB0_578:
	s_ashr_i32 s43, s42, 31
	s_lshl_b64 s[6:7], s[42:43], 19
	s_add_u32 s44, s20, s6
	s_addc_u32 s45, s21, s7
	s_and_b64 s[6:7], s[8:9], exec
	s_cselect_b32 s6, s45, s55
	s_cselect_b32 s7, s44, s54
	s_ashr_i32 s37, s36, 31
	s_lshl_b64 s[12:13], s[36:37], 19
	s_add_u32 s46, s31, s12
	s_addc_u32 s47, s38, s13
	s_and_b64 s[12:13], s[8:9], exec
	s_cselect_b32 s37, s47, s49
	s_cselect_b32 s43, s46, s48
	s_add_u32 s12, s54, 0x40080
	s_addc_u32 s13, s55, 0
	s_add_u32 s54, s48, 0x100
	v_mov_b32_e32 v0, 0
	s_addc_u32 s55, s49, 0
	s_mov_b32 s61, -2
	v_mov_b32_e32 v1, v0
	v_mov_b32_e32 v2, v0
	v_mov_b32_e32 v3, v0
	v_mov_b32_e32 v4, v0
	v_mov_b32_e32 v5, v0
	v_mov_b32_e32 v6, v0
	v_mov_b32_e32 v7, v0
	v_mov_b32_e32 v12, v0
	v_mov_b32_e32 v13, v0
	v_mov_b32_e32 v14, v0
	v_mov_b32_e32 v15, v0
	v_mov_b32_e32 v20, v0
	v_mov_b32_e32 v21, v0
	v_mov_b32_e32 v22, v0
	v_mov_b32_e32 v23, v0
	v_mov_b32_e32 v28, v0
	v_mov_b32_e32 v29, v0
	v_mov_b32_e32 v30, v0
	v_mov_b32_e32 v31, v0
	v_mov_b32_e32 v36, v0
	v_mov_b32_e32 v37, v0
	v_mov_b32_e32 v38, v0
	v_mov_b32_e32 v39, v0
	v_mov_b32_e32 v44, v0
	v_mov_b32_e32 v45, v0
	v_mov_b32_e32 v46, v0
	v_mov_b32_e32 v47, v0
	v_mov_b32_e32 v52, v0
	v_mov_b32_e32 v53, v0
	v_mov_b32_e32 v54, v0
	v_mov_b32_e32 v55, v0
	v_mov_b32_e32 v8, v0
	v_mov_b32_e32 v9, v0
	v_mov_b32_e32 v10, v0
	v_mov_b32_e32 v11, v0
	v_mov_b32_e32 v16, v0
	v_mov_b32_e32 v17, v0
	v_mov_b32_e32 v18, v0
	v_mov_b32_e32 v19, v0
	v_mov_b32_e32 v24, v0
	v_mov_b32_e32 v25, v0
	v_mov_b32_e32 v26, v0
	v_mov_b32_e32 v27, v0
	v_mov_b32_e32 v32, v0
	v_mov_b32_e32 v33, v0
	v_mov_b32_e32 v34, v0
	v_mov_b32_e32 v35, v0
	v_mov_b32_e32 v40, v0
	v_mov_b32_e32 v41, v0
	v_mov_b32_e32 v42, v0
	v_mov_b32_e32 v43, v0
	v_mov_b32_e32 v48, v0
	v_mov_b32_e32 v49, v0
	v_mov_b32_e32 v50, v0
	v_mov_b32_e32 v51, v0
	v_mov_b32_e32 v56, v0
	v_mov_b32_e32 v57, v0
	v_mov_b32_e32 v58, v0
	v_mov_b32_e32 v59, v0
	v_mov_b32_e32 v60, v0
	v_mov_b32_e32 v61, v0
	v_mov_b32_e32 v62, v0
	v_mov_b32_e32 v63, v0
	v_mov_b32_e32 v64, v0
	v_mov_b32_e32 v65, v0
	v_mov_b32_e32 v66, v0
	v_mov_b32_e32 v67, v0
	v_mov_b32_e32 v68, v0
	v_mov_b32_e32 v69, v0
	v_mov_b32_e32 v70, v0
	v_mov_b32_e32 v71, v0
	v_mov_b32_e32 v76, v0
	v_mov_b32_e32 v77, v0
	v_mov_b32_e32 v78, v0
	v_mov_b32_e32 v79, v0
	v_mov_b32_e32 v84, v0
	v_mov_b32_e32 v85, v0
	v_mov_b32_e32 v86, v0
	v_mov_b32_e32 v87, v0
	v_mov_b32_e32 v92, v0
	v_mov_b32_e32 v93, v0
	v_mov_b32_e32 v94, v0
	v_mov_b32_e32 v95, v0
	v_mov_b32_e32 v100, v0
	v_mov_b32_e32 v101, v0
	v_mov_b32_e32 v102, v0
	v_mov_b32_e32 v103, v0
	v_mov_b32_e32 v108, v0
	v_mov_b32_e32 v109, v0
	v_mov_b32_e32 v110, v0
	v_mov_b32_e32 v111, v0
	v_mov_b32_e32 v116, v0
	v_mov_b32_e32 v117, v0
	v_mov_b32_e32 v118, v0
	v_mov_b32_e32 v119, v0
	v_mov_b32_e32 v72, v0
	v_mov_b32_e32 v73, v0
	v_mov_b32_e32 v74, v0
	v_mov_b32_e32 v75, v0
	v_mov_b32_e32 v80, v0
	v_mov_b32_e32 v81, v0
	v_mov_b32_e32 v82, v0
	v_mov_b32_e32 v83, v0
	v_mov_b32_e32 v88, v0
	v_mov_b32_e32 v89, v0
	v_mov_b32_e32 v90, v0
	v_mov_b32_e32 v91, v0
	v_mov_b32_e32 v96, v0
	v_mov_b32_e32 v97, v0
	v_mov_b32_e32 v98, v0
	v_mov_b32_e32 v99, v0
	v_mov_b32_e32 v104, v0
	v_mov_b32_e32 v105, v0
	v_mov_b32_e32 v106, v0
	v_mov_b32_e32 v107, v0
	v_mov_b32_e32 v112, v0
	v_mov_b32_e32 v113, v0
	v_mov_b32_e32 v114, v0
	v_mov_b32_e32 v115, v0
	v_mov_b32_e32 v120, v0
	v_mov_b32_e32 v121, v0
	v_mov_b32_e32 v122, v0
	v_mov_b32_e32 v123, v0
	v_mov_b32_e32 v124, v0
	v_mov_b32_e32 v125, v0
	v_mov_b32_e32 v126, v0
	v_mov_b32_e32 v127, v0
	v_add_u32_e32 v254, 0x10000, v223
.LBB0_579:
	s_add_u32 s48, s12, 0xfffc0080
	s_addc_u32 s49, s13, -1
	s_add_i32 s62, 0, 0x10000
	s_cmp_eq_u32 s61, 12
	s_cselect_b32 s51, s6, s49
	s_cselect_b32 s50, s7, s48
	s_cselect_b32 s49, s37, s55
	s_cselect_b32 s48, s43, s54
	s_add_i32 s64, 0, 0x14000
	ds_read_b128 v[128:131], v254
	ds_read_b128 v[132:135], v254 offset:1024
	ds_read_b128 v[136:139], v254 offset:2048
	ds_read_b128 v[140:143], v254 offset:3072
	ds_read_b128 v[144:147], v254 offset:16384
	ds_read_b128 v[148:151], v254 offset:17408
	ds_read_b128 v[152:155], v254 offset:18432
	ds_read_b128 v[156:159], v254 offset:19456
	s_add_i32 m0, s40, 0xc000
	ds_read_b128 v[170:173], v226
	ds_read_b128 v[174:177], v226 offset:1024
	ds_read_b128 v[178:181], v226 offset:2048
	ds_read_b128 v[182:185], v226 offset:3072
	ds_read_b128 v[204:207], v226 offset:4096
	ds_read_b128 v[228:231], v226 offset:5120
	ds_read_b128 v[232:235], v226 offset:6144
	ds_read_b128 v[236:239], v226 offset:7168
	global_load_lds_dwordx4 v166, s[12:13]
	s_add_i32 m0, s40, 0xe000
	s_nop 0
	global_load_lds_dwordx4 v168, s[12:13]
	s_waitcnt vmcnt(8)
	s_waitcnt lgkmcnt(0)
	s_barrier
	s_setprio 1
	s_waitcnt lgkmcnt(0)
	v_mfma_f32_16x16x32_bf16 v[124:127], v[128:131], v[170:173], v[124:127]
	v_mfma_f32_16x16x32_bf16 v[120:123], v[136:139], v[170:173], v[120:123]
	v_mfma_f32_16x16x32_bf16 v[112:115], v[128:131], v[178:181], v[112:115]
	v_mfma_f32_16x16x32_bf16 v[104:107], v[136:139], v[178:181], v[104:107]
	v_mfma_f32_16x16x32_bf16 v[96:99], v[128:131], v[204:207], v[96:99]
	v_mfma_f32_16x16x32_bf16 v[88:91], v[136:139], v[204:207], v[88:91]
	v_mfma_f32_16x16x32_bf16 v[80:83], v[128:131], v[232:235], v[80:83]
	v_mfma_f32_16x16x32_bf16 v[72:75], v[136:139], v[232:235], v[72:75]
	v_mfma_f32_16x16x32_bf16 v[124:127], v[132:135], v[174:177], v[124:127]
	v_mfma_f32_16x16x32_bf16 v[120:123], v[140:143], v[174:177], v[120:123]
	v_mfma_f32_16x16x32_bf16 v[112:115], v[132:135], v[182:185], v[112:115]
	v_mfma_f32_16x16x32_bf16 v[104:107], v[140:143], v[182:185], v[104:107]
	v_mfma_f32_16x16x32_bf16 v[96:99], v[132:135], v[228:231], v[96:99]
	v_mfma_f32_16x16x32_bf16 v[88:91], v[140:143], v[228:231], v[88:91]
	v_mfma_f32_16x16x32_bf16 v[80:83], v[132:135], v[236:239], v[80:83]
	v_mfma_f32_16x16x32_bf16 v[72:75], v[140:143], v[236:239], v[72:75]
	s_setprio 0
	s_setprio 1
	v_mfma_f32_16x16x32_bf16 v[116:119], v[144:147], v[170:173], v[116:119]
	v_mfma_f32_16x16x32_bf16 v[108:111], v[152:155], v[170:173], v[108:111]
	v_mfma_f32_16x16x32_bf16 v[100:103], v[144:147], v[178:181], v[100:103]
	v_mfma_f32_16x16x32_bf16 v[92:95], v[152:155], v[178:181], v[92:95]
	v_mfma_f32_16x16x32_bf16 v[84:87], v[144:147], v[204:207], v[84:87]
	v_mfma_f32_16x16x32_bf16 v[76:79], v[152:155], v[204:207], v[76:79]
	v_mfma_f32_16x16x32_bf16 v[68:71], v[144:147], v[232:235], v[68:71]
	v_mfma_f32_16x16x32_bf16 v[64:67], v[152:155], v[232:235], v[64:67]
	v_mfma_f32_16x16x32_bf16 v[116:119], v[148:151], v[174:177], v[116:119]
	v_mfma_f32_16x16x32_bf16 v[108:111], v[156:159], v[174:177], v[108:111]
	v_mfma_f32_16x16x32_bf16 v[100:103], v[148:151], v[182:185], v[100:103]
	v_mfma_f32_16x16x32_bf16 v[92:95], v[156:159], v[182:185], v[92:95]
	v_mfma_f32_16x16x32_bf16 v[84:87], v[148:151], v[228:231], v[84:87]
	v_mfma_f32_16x16x32_bf16 v[76:79], v[156:159], v[228:231], v[76:79]
	v_mfma_f32_16x16x32_bf16 v[68:71], v[148:151], v[236:239], v[68:71]
	v_mfma_f32_16x16x32_bf16 v[64:67], v[156:159], v[236:239], v[64:67]
	s_setprio 0
	s_barrier
	s_add_i32 s62, s62, s39
	s_mov_b32 m0, s62
	ds_read_b128 v[170:173], v226 offset:16384
	ds_read_b128 v[174:177], v226 offset:17408
	ds_read_b128 v[178:181], v226 offset:18432
	ds_read_b128 v[182:185], v226 offset:19456
	ds_read_b128 v[204:207], v226 offset:20480
	ds_read_b128 v[228:231], v226 offset:21504
	ds_read_b128 v[232:235], v226 offset:22528
	ds_read_b128 v[236:239], v226 offset:23552
	global_load_lds_dwordx4 v190, s[48:49]
	s_add_i32 m0, s62, 0x2000
	s_add_u32 s62, s48, 0x40000
	s_addc_u32 s63, s49, 0
	s_add_i32 s64, s64, s39
	global_load_lds_dwordx4 v160, s[48:49]
	s_mov_b32 m0, s64
	s_nop 0
	global_load_lds_dwordx4 v190, s[62:63]
	s_add_i32 m0, s64, 0x2000
	s_nop 0
	global_load_lds_dwordx4 v160, s[62:63]
	s_mov_b32 m0, s40
	s_nop 0
	global_load_lds_dwordx4 v164, s[50:51]
	s_mov_b32 m0, s41
	s_nop 0
	global_load_lds_dwordx4 v162, s[50:51]
	s_waitcnt vmcnt(8)
	s_waitcnt lgkmcnt(0)
	s_barrier
	s_setprio 1
	s_waitcnt lgkmcnt(0)
	v_mfma_f32_16x16x32_bf16 v[60:63], v[128:131], v[170:173], v[60:63]
	v_mfma_f32_16x16x32_bf16 v[56:59], v[136:139], v[170:173], v[56:59]
	v_mfma_f32_16x16x32_bf16 v[48:51], v[128:131], v[178:181], v[48:51]
	v_mfma_f32_16x16x32_bf16 v[40:43], v[136:139], v[178:181], v[40:43]
	v_mfma_f32_16x16x32_bf16 v[32:35], v[128:131], v[204:207], v[32:35]
	v_mfma_f32_16x16x32_bf16 v[24:27], v[136:139], v[204:207], v[24:27]
	v_mfma_f32_16x16x32_bf16 v[16:19], v[128:131], v[232:235], v[16:19]
	v_mfma_f32_16x16x32_bf16 v[8:11], v[136:139], v[232:235], v[8:11]
	v_mfma_f32_16x16x32_bf16 v[60:63], v[132:135], v[174:177], v[60:63]
	v_mfma_f32_16x16x32_bf16 v[56:59], v[140:143], v[174:177], v[56:59]
	v_mfma_f32_16x16x32_bf16 v[48:51], v[132:135], v[182:185], v[48:51]
	v_mfma_f32_16x16x32_bf16 v[40:43], v[140:143], v[182:185], v[40:43]
	v_mfma_f32_16x16x32_bf16 v[32:35], v[132:135], v[228:231], v[32:35]
	v_mfma_f32_16x16x32_bf16 v[24:27], v[140:143], v[228:231], v[24:27]
	v_mfma_f32_16x16x32_bf16 v[16:19], v[132:135], v[236:239], v[16:19]
	v_mfma_f32_16x16x32_bf16 v[8:11], v[140:143], v[236:239], v[8:11]
	s_setprio 0
	s_setprio 1
	v_mfma_f32_16x16x32_bf16 v[52:55], v[144:147], v[170:173], v[52:55]
	v_mfma_f32_16x16x32_bf16 v[44:47], v[152:155], v[170:173], v[44:47]
	v_mfma_f32_16x16x32_bf16 v[36:39], v[144:147], v[178:181], v[36:39]
	v_mfma_f32_16x16x32_bf16 v[28:31], v[152:155], v[178:181], v[28:31]
	v_mfma_f32_16x16x32_bf16 v[20:23], v[144:147], v[204:207], v[20:23]
	v_mfma_f32_16x16x32_bf16 v[12:15], v[152:155], v[204:207], v[12:15]
	v_mfma_f32_16x16x32_bf16 v[4:7], v[144:147], v[232:235], v[4:7]
	v_mfma_f32_16x16x32_bf16 v[0:3], v[152:155], v[232:235], v[0:3]
	v_mfma_f32_16x16x32_bf16 v[52:55], v[148:151], v[174:177], v[52:55]
	v_mfma_f32_16x16x32_bf16 v[44:47], v[156:159], v[174:177], v[44:47]
	v_mfma_f32_16x16x32_bf16 v[36:39], v[148:151], v[182:185], v[36:39]
	v_mfma_f32_16x16x32_bf16 v[28:31], v[156:159], v[182:185], v[28:31]
	v_mfma_f32_16x16x32_bf16 v[20:23], v[148:151], v[228:231], v[20:23]
	v_mfma_f32_16x16x32_bf16 v[12:15], v[156:159], v[228:231], v[12:15]
	v_mfma_f32_16x16x32_bf16 v[4:7], v[148:151], v[236:239], v[4:7]
	v_mfma_f32_16x16x32_bf16 v[0:3], v[156:159], v[236:239], v[0:3]
	s_setprio 0
	s_barrier
	s_add_i32 s62, 0, 0x18000
	s_add_i32 s63, 0, 0x1c000
	ds_read_b128 v[128:131], v254 offset:32768
	ds_read_b128 v[132:135], v254 offset:33792
	ds_read_b128 v[136:139], v254 offset:34816
	ds_read_b128 v[140:143], v254 offset:35840
	ds_read_b128 v[144:147], v254 offset:49152
	ds_read_b128 v[148:151], v254 offset:50176
	ds_read_b128 v[152:155], v254 offset:51200
	ds_read_b128 v[156:159], v254 offset:52224
	s_add_u32 s100, s50, s74
	s_addc_u32 s101, s51, s75
	s_add_u32 s50, s50, 0x40000
	s_addc_u32 s51, s51, 0
	s_mov_b32 m0, s56
	ds_read_b128 v[170:173], v226 offset:32768
	ds_read_b128 v[174:177], v226 offset:33792
	ds_read_b128 v[178:181], v226 offset:34816
	ds_read_b128 v[182:185], v226 offset:35840
	ds_read_b128 v[204:207], v226 offset:36864
	ds_read_b128 v[228:231], v226 offset:37888
	ds_read_b128 v[232:235], v226 offset:38912
	ds_read_b128 v[236:239], v226 offset:39936
	global_load_lds_dwordx4 v164, s[50:51]
	s_mov_b32 m0, s57
	s_nop 0
	global_load_lds_dwordx4 v162, s[50:51]
	s_waitcnt vmcnt(8)
	s_waitcnt lgkmcnt(0)
	s_barrier
	s_setprio 1
	s_waitcnt lgkmcnt(0)
	v_mfma_f32_16x16x32_bf16 v[124:127], v[128:131], v[170:173], v[124:127]
	v_mfma_f32_16x16x32_bf16 v[120:123], v[136:139], v[170:173], v[120:123]
	v_mfma_f32_16x16x32_bf16 v[112:115], v[128:131], v[178:181], v[112:115]
	v_mfma_f32_16x16x32_bf16 v[104:107], v[136:139], v[178:181], v[104:107]
	v_mfma_f32_16x16x32_bf16 v[96:99], v[128:131], v[204:207], v[96:99]
	v_mfma_f32_16x16x32_bf16 v[88:91], v[136:139], v[204:207], v[88:91]
	v_mfma_f32_16x16x32_bf16 v[80:83], v[128:131], v[232:235], v[80:83]
	v_mfma_f32_16x16x32_bf16 v[72:75], v[136:139], v[232:235], v[72:75]
	v_mfma_f32_16x16x32_bf16 v[124:127], v[132:135], v[174:177], v[124:127]
	v_mfma_f32_16x16x32_bf16 v[120:123], v[140:143], v[174:177], v[120:123]
	v_mfma_f32_16x16x32_bf16 v[112:115], v[132:135], v[182:185], v[112:115]
	v_mfma_f32_16x16x32_bf16 v[104:107], v[140:143], v[182:185], v[104:107]
	v_mfma_f32_16x16x32_bf16 v[96:99], v[132:135], v[228:231], v[96:99]
	v_mfma_f32_16x16x32_bf16 v[88:91], v[140:143], v[228:231], v[88:91]
	v_mfma_f32_16x16x32_bf16 v[80:83], v[132:135], v[236:239], v[80:83]
	v_mfma_f32_16x16x32_bf16 v[72:75], v[140:143], v[236:239], v[72:75]
	s_setprio 0
	s_setprio 1
	v_mfma_f32_16x16x32_bf16 v[116:119], v[144:147], v[170:173], v[116:119]
	v_mfma_f32_16x16x32_bf16 v[108:111], v[152:155], v[170:173], v[108:111]
	v_mfma_f32_16x16x32_bf16 v[100:103], v[144:147], v[178:181], v[100:103]
	v_mfma_f32_16x16x32_bf16 v[92:95], v[152:155], v[178:181], v[92:95]
	v_mfma_f32_16x16x32_bf16 v[84:87], v[144:147], v[204:207], v[84:87]
	v_mfma_f32_16x16x32_bf16 v[76:79], v[152:155], v[204:207], v[76:79]
	v_mfma_f32_16x16x32_bf16 v[68:71], v[144:147], v[232:235], v[68:71]
	v_mfma_f32_16x16x32_bf16 v[64:67], v[152:155], v[232:235], v[64:67]
	v_mfma_f32_16x16x32_bf16 v[116:119], v[148:151], v[174:177], v[116:119]
	v_mfma_f32_16x16x32_bf16 v[108:111], v[156:159], v[174:177], v[108:111]
	v_mfma_f32_16x16x32_bf16 v[100:103], v[148:151], v[182:185], v[100:103]
	v_mfma_f32_16x16x32_bf16 v[92:95], v[156:159], v[182:185], v[92:95]
	v_mfma_f32_16x16x32_bf16 v[84:87], v[148:151], v[228:231], v[84:87]
	v_mfma_f32_16x16x32_bf16 v[76:79], v[156:159], v[228:231], v[76:79]
	v_mfma_f32_16x16x32_bf16 v[68:71], v[148:151], v[236:239], v[68:71]
	v_mfma_f32_16x16x32_bf16 v[64:67], v[156:159], v[236:239], v[64:67]
	s_setprio 0
	s_barrier
	s_add_u32 vcc_lo, s48, s74
	s_addc_u32 vcc_hi, s49, s75
	s_add_i32 s50, s62, s39
	s_mov_b32 m0, s50
	ds_read_b128 v[170:173], v226 offset:49152
	ds_read_b128 v[174:177], v226 offset:50176
	ds_read_b128 v[178:181], v226 offset:51200
	ds_read_b128 v[182:185], v226 offset:52224
	ds_read_b128 v[204:207], v226 offset:53248
	ds_read_b128 v[228:231], v226 offset:54272
	ds_read_b128 v[232:235], v226 offset:55296
	ds_read_b128 v[236:239], v226 offset:56320
	global_load_lds_dwordx4 v190, vcc
	s_add_i32 m0, s50, 0x2000
	s_add_u32 s48, s48, 0x40080
	s_addc_u32 s49, s49, 0
	s_add_i32 s50, s63, s39
	global_load_lds_dwordx4 v160, vcc
	s_mov_b32 m0, s50
	s_nop 0
	global_load_lds_dwordx4 v190, s[48:49]
	s_add_i32 m0, s50, 0x2000
	s_nop 0
	global_load_lds_dwordx4 v160, s[48:49]
	s_mov_b32 m0, s58
	s_nop 0
	global_load_lds_dwordx4 v164, s[100:101]
	s_mov_b32 m0, s59
	s_nop 0
	global_load_lds_dwordx4 v162, s[100:101]
	s_waitcnt vmcnt(8)
	s_waitcnt lgkmcnt(0)
	s_barrier
	s_setprio 1
	s_waitcnt lgkmcnt(0)
	v_mfma_f32_16x16x32_bf16 v[60:63], v[128:131], v[170:173], v[60:63]
	v_mfma_f32_16x16x32_bf16 v[56:59], v[136:139], v[170:173], v[56:59]
	v_mfma_f32_16x16x32_bf16 v[48:51], v[128:131], v[178:181], v[48:51]
	v_mfma_f32_16x16x32_bf16 v[40:43], v[136:139], v[178:181], v[40:43]
	v_mfma_f32_16x16x32_bf16 v[32:35], v[128:131], v[204:207], v[32:35]
	v_mfma_f32_16x16x32_bf16 v[24:27], v[136:139], v[204:207], v[24:27]
	v_mfma_f32_16x16x32_bf16 v[16:19], v[128:131], v[232:235], v[16:19]
	v_mfma_f32_16x16x32_bf16 v[8:11], v[136:139], v[232:235], v[8:11]
	v_mfma_f32_16x16x32_bf16 v[60:63], v[132:135], v[174:177], v[60:63]
	v_mfma_f32_16x16x32_bf16 v[56:59], v[140:143], v[174:177], v[56:59]
	v_mfma_f32_16x16x32_bf16 v[48:51], v[132:135], v[182:185], v[48:51]
	v_mfma_f32_16x16x32_bf16 v[40:43], v[140:143], v[182:185], v[40:43]
	v_mfma_f32_16x16x32_bf16 v[32:35], v[132:135], v[228:231], v[32:35]
	v_mfma_f32_16x16x32_bf16 v[24:27], v[140:143], v[228:231], v[24:27]
	v_mfma_f32_16x16x32_bf16 v[16:19], v[132:135], v[236:239], v[16:19]
	v_mfma_f32_16x16x32_bf16 v[8:11], v[140:143], v[236:239], v[8:11]
	s_setprio 0
	s_setprio 1
	v_mfma_f32_16x16x32_bf16 v[52:55], v[144:147], v[170:173], v[52:55]
	v_mfma_f32_16x16x32_bf16 v[44:47], v[152:155], v[170:173], v[44:47]
	v_mfma_f32_16x16x32_bf16 v[36:39], v[144:147], v[178:181], v[36:39]
	v_mfma_f32_16x16x32_bf16 v[28:31], v[152:155], v[178:181], v[28:31]
	v_mfma_f32_16x16x32_bf16 v[20:23], v[144:147], v[204:207], v[20:23]
	v_mfma_f32_16x16x32_bf16 v[12:15], v[152:155], v[204:207], v[12:15]
	v_mfma_f32_16x16x32_bf16 v[4:7], v[144:147], v[232:235], v[4:7]
	v_mfma_f32_16x16x32_bf16 v[0:3], v[152:155], v[232:235], v[0:3]
	v_mfma_f32_16x16x32_bf16 v[52:55], v[148:151], v[174:177], v[52:55]
	v_mfma_f32_16x16x32_bf16 v[44:47], v[156:159], v[174:177], v[44:47]
	v_mfma_f32_16x16x32_bf16 v[36:39], v[148:151], v[182:185], v[36:39]
	v_mfma_f32_16x16x32_bf16 v[28:31], v[156:159], v[182:185], v[28:31]
	v_mfma_f32_16x16x32_bf16 v[20:23], v[148:151], v[228:231], v[20:23]
	v_mfma_f32_16x16x32_bf16 v[12:15], v[156:159], v[228:231], v[12:15]
	v_mfma_f32_16x16x32_bf16 v[4:7], v[148:151], v[236:239], v[4:7]
	v_mfma_f32_16x16x32_bf16 v[0:3], v[156:159], v[236:239], v[0:3]
	s_setprio 0
	s_barrier
	s_add_i32 s61, s61, 2
	s_add_u32 s12, s12, 0x100
	s_addc_u32 s13, s13, 0
	s_add_u32 s54, s54, 0x100
	s_addc_u32 s55, s55, 0
	s_cmp_gt_u32 s61, 13
	s_cbranch_scc0 .LBB0_579
	s_and_b64 vcc, exec, s[34:35]
	s_cbranch_vccz .LBB0_582
	s_barrier

	.amdhsa_kernel _Z10fwd_kernel4Args
		.amdhsa_group_segment_fixed_size 0
		.amdhsa_private_segment_fixed_size 0
		.amdhsa_kernarg_size 384
		.amdhsa_user_sgpr_count 2
		.amdhsa_user_sgpr_dispatch_ptr 0
		.amdhsa_user_sgpr_queue_ptr 0
		.amdhsa_user_sgpr_kernarg_segment_ptr 1
		.amdhsa_user_sgpr_dispatch_id 0
		.amdhsa_user_sgpr_kernarg_preload_length 0
		.amdhsa_user_sgpr_kernarg_preload_offset 0
		.amdhsa_user_sgpr_private_segment_size 0
		.amdhsa_uses_dynamic_stack 0
		.amdhsa_enable_private_segment 0
		.amdhsa_system_sgpr_workgroup_id_x 1
		.amdhsa_system_sgpr_workgroup_id_y 0
		.amdhsa_system_sgpr_workgroup_id_z 0
		.amdhsa_system_sgpr_workgroup_info 0
		.amdhsa_system_vgpr_workitem_id 2
		.amdhsa_next_free_vgpr 256
		.amdhsa_next_free_sgpr 102
		.amdhsa_accum_offset 256
		.amdhsa_reserve_vcc 1
		.amdhsa_float_round_mode_32 0
		.amdhsa_float_round_mode_16_64 0
		.amdhsa_float_denorm_mode_32 3
		.amdhsa_float_denorm_mode_16_64 3
		.amdhsa_dx10_clamp 1
		.amdhsa_ieee_mode 1
		.amdhsa_fp16_overflow 0
		.amdhsa_tg_split 0
		.amdhsa_exception_fp_ieee_invalid_op 0
		.amdhsa_exception_fp_denorm_src 0
		.amdhsa_exception_fp_ieee_div_zero 0
		.amdhsa_exception_fp_ieee_overflow 0
		.amdhsa_exception_fp_ieee_underflow 0
		.amdhsa_exception_fp_ieee_inexact 0
		.amdhsa_exception_int_div_zero 0
	.end_amdhsa_kernel

amdhsa.kernels:
  - .agpr_count:     0
    .args:
      - .offset:         0
        .size:           128
        .value_kind:     by_value
      - .offset:         128
        .size:           4
        .value_kind:     hidden_block_count_x
      - .offset:         132
        .size:           4
        .value_kind:     hidden_block_count_y
      - .offset:         136
        .size:           4
        .value_kind:     hidden_block_count_z
      - .offset:         140
        .size:           2
        .value_kind:     hidden_group_size_x
      - .offset:         142
        .size:           2
        .value_kind:     hidden_group_size_y
      - .offset:         144
        .size:           2
        .value_kind:     hidden_group_size_z
      - .offset:         146
        .size:           2
        .value_kind:     hidden_remainder_x
      - .offset:         148
        .size:           2
        .value_kind:     hidden_remainder_y
      - .offset:         150
        .size:           2
        .value_kind:     hidden_remainder_z
      - .offset:         168
        .size:           8
        .value_kind:     hidden_global_offset_x
      - .offset:         176
        .size:           8
        .value_kind:     hidden_global_offset_y
      - .offset:         184
        .size:           8
        .value_kind:     hidden_global_offset_z
      - .offset:         192
        .size:           2
        .value_kind:     hidden_grid_dims
      - .offset:         216
        .size:           8
        .value_kind:     hidden_multigrid_sync_arg
      - .offset:         248
        .size:           4
        .value_kind:     hidden_dynamic_lds_size
    .group_segment_fixed_size: 0
    .kernarg_segment_align: 8
    .kernarg_segment_size: 384
    .language:       OpenCL C
    .language_version:
      - 2
      - 0
    .max_flat_workgroup_size: 512
    .name:           _Z10fwd_kernel4Args
    .private_segment_fixed_size: 0
    .sgpr_count:     108
    .sgpr_spill_count: 92
    .symbol:         _Z10fwd_kernel4Args.kd
    .uniform_work_group_size: 1
    .uses_dynamic_stack: false
    .vgpr_count:     256
    .vgpr_spill_count: 0
    .wavefront_size: 64
